# variant: odd workgroups run conv, FFT stage 1, pool (instead of conv, pool, FFT stage 1)
# speedup vs baseline: 1.0057x; 1.0057x over previous
; __global__ void __launch_bounds__(512, 2) fwd_megakernel(Params p_) {
;     ...
;                     u32x4 zws[8];
; #pragma unroll
;                     for (int k = 0; k < 8; ++k) { const int o = k * 512 + tid, r = o >> 5, chl = o & 31, ch = g * 32 + chl; zws[k] = *(const u32x4*)(H + SEG_P + (size_t)(R0 + r) * LDP + 1024 + ch * 8); }
;                     const int chl_ = tid & 31, ch_ = g * 32 + chl_;
;                     const f32x4 b0 = *(const f32x4*)(bg + ch_ * 8), b1 = *(const f32x4*)(bg + ch_ * 8 + 4), q0 = *(const f32x4*)(psc + ch_ * 8), q1 = *(const f32x4*)(psc + ch_ * 8 + 4);
; #pragma unroll
;                     for (int k = 0; k < 8; ++k) {
;                         const int o = k * 512 + tid, r = o >> 5, chl = o & 31, t = t0 + r, ch = g * 32 + chl;
.LBB0_316:
	s_cmp_eq_u32 s101, 3
	s_cbranch_scc0 .Lp2_c316
	v_readlane_b32 s2, v253, 15
	v_readlane_b32 s3, v253, 16
	s_nop 1
	v_cndmask_b32_e64 v0, 0, 1, s[2:3]
	v_cmp_ne_u32_e64 s[8:9], 1, v0
	v_add_u32_e32 v37, 0x200, v48
	v_add_u32_e32 v52, 0x400, v48
	v_add_u32_e32 v53, 0x600, v48
	v_add_u32_e32 v54, 0x800, v48
	v_add_u32_e32 v55, 0xa00, v48
	v_add_u32_e32 v56, 0xc00, v48
	v_add_u32_e32 v57, 0xe00, v48
	s_branch .LBB0_475

; #define LAS __attribute__((address_space(3)))
; __device__ __forceinline__ void unpack8(u32x4 w, f32x4& a, f32x4& b) { a = (f32x4){bf_lo(w.x), bf_hi(w.x), bf_lo(w.y), bf_hi(w.y)}; b = (f32x4){bf_lo(w.z), bf_hi(w.z), bf_lo(w.w), bf_hi(w.w)}; }
; __global__ void __launch_bounds__(512, 2) fwd_megakernel(Params p_) {
;     ...
; #pragma unroll 4
;                         for (int j = 0; j < 31; ++j) {
;                             f32x4 v0, v1; unpack8(*(const LAS u32x4*)(VT + (i + j) * 1024 + lane * 16), v0, v1);
;                             const f32x4 w0 = *(const LAS f32x4*)(WD + j * 512 + 8 * lane), w1 = *(const LAS f32x4*)(WD + j * 512 + 8 * lane + 4);
;                             a0 += w0 * v0; a1 += w1 * v1;
;                         }
;     ...
;             {
;                 const float* bg = p->in[I_BG] + l * 1024; const float* psc = p->in[I_PSC] + l * 1024;
;                 for (int rb = bid; rb < M_TOK / 128; rb += G) {
;                 const int R0 = rb * 128; int base, S; seq_of_row(R0, base, S); const int t0 = R0 - base;
;                 for (int g = 0; g < 4; ++g) {
;                     const int hw = 1 << g, NR = 128 + 2 * hw;
;                     __syncthreads();
;                     for (int idx = tid; idx < NR * 32; idx += 512) { const int q = idx >> 5, c16 = idx & 31, tt = t0 - hw + q;
;                         u32x4 v = {0u, 0u, 0u, 0u}; if (tt >= 0 && tt < S) v = *(const u32x4*)(H + SEG_P + (size_t)(base + tt) * LDP + g * 256 + c16 * 8);
;                         *(LAS u32x4*)(lds + q * 512 + c16 * 16) = v; }
;                     __syncthreads();
;                     u32x4 zws[8];
; #pragma unroll
;                     for (int k = 0; k < 8; ++k) { const int o = k * 512 + tid, r = o >> 5, chl = o & 31, ch = g * 32 + chl; zws[k] = *(const u32x4*)(H + SEG_P + (size_t)(R0 + r) * LDP + 1024 + ch * 8); }
;                     const int chl_ = tid & 31, ch_ = g * 32 + chl_;
;                     const f32x4 b0 = *(const f32x4*)(bg + ch_ * 8), b1 = *(const f32x4*)(bg + ch_ * 8 + 4), q0 = *(const f32x4*)(psc + ch_ * 8), q1 = *(const f32x4*)(psc + ch_ * 8 + 4);
.LBB0_473:
	v_add_u32_e32 v87, 0, v85
	ds_read_b128 v[42:45], v87 offset:63488
	v_add_u32_e32 v86, 0, v84
	s_cmp_eq_u32 s26, 0
	s_waitcnt lgkmcnt(0)
	v_lshlrev_b32_e32 v46, 16, v42
	v_and_b32_e32 v47, 0xffff0000, v42
	v_lshlrev_b32_e32 v50, 16, v43
	v_and_b32_e32 v51, 0xffff0000, v43
	v_lshlrev_b32_e32 v92, 16, v44
	v_and_b32_e32 v93, 0xffff0000, v44
	v_lshlrev_b32_e32 v94, 16, v45
	v_and_b32_e32 v95, 0xffff0000, v45
	ds_read_b128 v[42:45], v86
	ds_read_b128 v[88:91], v86 offset:16
	s_waitcnt lgkmcnt(1)
	v_pk_fma_f32 v[44:45], v[44:45], v[50:51], v[30:31]
	v_pk_fma_f32 v[42:43], v[42:43], v[46:47], v[28:29]
	ds_read_b128 v[28:31], v87 offset:64512
	s_waitcnt lgkmcnt(1)
	v_pk_fma_f32 v[46:47], v[90:91], v[94:95], v[34:35]
	v_pk_fma_f32 v[50:51], v[88:89], v[92:93], v[32:33]
	s_waitcnt lgkmcnt(0)
	v_lshlrev_b32_e32 v88, 16, v28
	v_and_b32_e32 v89, 0xffff0000, v28
	v_lshlrev_b32_e32 v90, 16, v29
	v_and_b32_e32 v91, 0xffff0000, v29
	v_lshlrev_b32_e32 v92, 16, v30
	v_and_b32_e32 v93, 0xffff0000, v30
	v_lshlrev_b32_e32 v94, 16, v31
	v_and_b32_e32 v95, 0xffff0000, v31
	ds_read_b128 v[28:31], v86 offset:2048
	ds_read_b128 v[32:35], v86 offset:2064
	s_waitcnt lgkmcnt(1)
	v_pk_fma_f32 v[88:89], v[28:29], v[88:89], v[42:43]
	v_add_u32_e32 v28, 0x10000, v87
	v_pk_fma_f32 v[42:43], v[30:31], v[90:91], v[44:45]
	ds_read_b128 v[28:31], v28
	s_waitcnt lgkmcnt(1)
	v_pk_fma_f32 v[50:51], v[32:33], v[92:93], v[50:51]
	v_pk_fma_f32 v[46:47], v[34:35], v[94:95], v[46:47]
	s_waitcnt lgkmcnt(0)
	v_lshlrev_b32_e32 v44, 16, v28
	v_and_b32_e32 v45, 0xffff0000, v28
	v_lshlrev_b32_e32 v90, 16, v29
	v_and_b32_e32 v91, 0xffff0000, v29
	v_lshlrev_b32_e32 v92, 16, v30
	v_and_b32_e32 v93, 0xffff0000, v30
	v_lshlrev_b32_e32 v94, 16, v31
	v_and_b32_e32 v95, 0xffff0000, v31
	ds_read_b128 v[28:31], v86 offset:4096
	ds_read_b128 v[32:35], v86 offset:4112
	s_waitcnt lgkmcnt(1)
	v_pk_fma_f32 v[42:43], v[30:31], v[90:91], v[42:43]
	v_pk_fma_f32 v[44:45], v[28:29], v[44:45], v[88:89]
	s_waitcnt lgkmcnt(0)
	v_pk_fma_f32 v[46:47], v[34:35], v[94:95], v[46:47]
	v_pk_fma_f32 v[50:51], v[32:33], v[92:93], v[50:51]
	s_cbranch_scc1 .LBB0_472
	v_add_u32_e32 v28, 0x10400, v87
	ds_read_b128 v[28:31], v28
	ds_read_b128 v[32:35], v86 offset:6144
	ds_read_b128 v[86:89], v86 offset:6160
	s_add_i32 s26, s26, -4
	v_add_u32_e32 v85, 0x1000, v85
	s_waitcnt lgkmcnt(2)
	v_lshlrev_b32_e32 v90, 16, v28
	v_and_b32_e32 v91, 0xffff0000, v28
	v_lshlrev_b32_e32 v28, 16, v29
	v_and_b32_e32 v29, 0xffff0000, v29
	v_lshlrev_b32_e32 v92, 16, v30
	v_and_b32_e32 v93, 0xffff0000, v30
	v_lshlrev_b32_e32 v94, 16, v31
	v_and_b32_e32 v95, 0xffff0000, v31
	s_waitcnt lgkmcnt(1)
	v_pk_fma_f32 v[30:31], v[34:35], v[28:29], v[42:43]
	v_pk_fma_f32 v[28:29], v[32:33], v[90:91], v[44:45]
	s_waitcnt lgkmcnt(0)
	v_pk_fma_f32 v[34:35], v[88:89], v[94:95], v[46:47]
	v_pk_fma_f32 v[32:33], v[86:87], v[92:93], v[50:51]
	v_add_u32_e32 v84, 0x2000, v84
	s_cbranch_execnz .LBB0_473
	s_branch .LBB0_470
.LBB0_475:
	s_cmp_eq_u32 s101, 1
	s_cbranch_scc0 .Lp2_cont
	s_mov_b32 s101, 3
	s_branch .Lp2_fft1
.Lp2_cont:
	s_and_b64 vcc, exec, s[8:9]
	s_cbranch_vccnz .LBB0_504
	v_readlane_b32 s0, v255, 10
	v_readlane_b32 s1, v255, 11
	s_load_dwordx4 s[12:15], s[0:1], 0x50
	v_readlane_b32 s0, v255, 6
	s_lshl_b32 s72, s0, 10
	s_lshl_b64 s[2:3], s[72:73], 2
	s_waitcnt vmcnt(0)
	v_lshlrev_b32_e32 v0, 3, v48
	s_waitcnt lgkmcnt(0)
	s_add_u32 s10, s12, s2
	v_and_b32_e32 v76, 0xf8, v0
	s_addc_u32 s11, s13, s3
	v_and_b32_e32 v0, 31, v48
	s_add_u32 s12, s14, s2
	v_lshlrev_b32_e32 v184, 4, v0
	s_addc_u32 s13, s15, s3
	v_lshlrev_b32_e32 v77, 3, v0
	v_lshl_add_u64 v[0:1], s[6:7], 0, v[184:185]
	s_mov_b64 s[2:3], 0x14d2a000
	v_ashrrev_i32_e32 v80, 5, v48
	v_lshl_add_u64 v[50:51], v[0:1], 0, s[2:3]
	v_ashrrev_i32_e32 v81, 5, v37
	v_lshl_or_b32 v0, v80, 9, v184
	v_ashrrev_i32_e32 v82, 5, v52
	v_add_u32_e32 v87, 0, v0
	v_lshl_or_b32 v0, v81, 9, v184
	v_ashrrev_i32_e32 v83, 5, v53
	v_add_u32_e32 v88, 0, v0
	v_lshl_or_b32 v0, v82, 9, v184
	v_ashrrev_i32_e32 v84, 5, v54
	v_add_u32_e32 v89, 0, v0
	v_lshl_or_b32 v0, v83, 9, v184
	v_ashrrev_i32_e32 v85, 5, v55
	v_add_u32_e32 v90, 0, v0
	v_lshl_or_b32 v0, v84, 9, v184
	v_ashrrev_i32_e32 v86, 5, v56
	v_add_u32_e32 v91, 0, v0
	v_lshl_or_b32 v0, v85, 9, v184
	v_ashrrev_i32_e32 v79, 5, v57
	v_add_u32_e32 v92, 0, v0
	v_lshl_or_b32 v0, v86, 9, v184
	v_add_u32_e32 v93, 0, v0
	v_lshl_or_b32 v0, v79, 9, v184
	v_add_u32_e32 v78, 0, v184
	v_add_u32_e32 v94, 0, v0
	v_readlane_b32 s2, v253, 7
	v_readlane_b32 s1, v255, 7
	v_readlane_b32 s3, v253, 8
